# v15 + grid barrier release detected by polling the cross-XCD arrival counter (TOP >= (gen+1)*nx) instead of waiting for the last leader to bump a separate generation word
# speedup vs baseline: 1.0064x; 1.0064x over previous
.LBB0_116:
	s_or_b64 exec, exec, s[8:9]
	v_cvt_f32_u32_e32 v4, v2
	s_waitcnt vmcnt(0)
	v_readfirstlane_b32 s6, v3
	v_sub_u32_e32 v3, 0, v2
	v_rcp_iflag_f32_e32 v4, v4
	v_add_u32_e32 v5, s6, v1
	v_mul_f32_e32 v4, 0x4f7ffffe, v4
	v_cvt_u32_f32_e32 v4, v4
	v_mul_lo_u32 v1, v3, v4
	v_mul_hi_u32 v1, v4, v1
	v_add_u32_e32 v1, v4, v1
	v_mul_hi_u32 v1, v5, v1
	v_mul_lo_u32 v3, v1, v2
	v_sub_u32_e32 v3, v5, v3
	v_add_u32_e32 v4, 1, v1
	v_cmp_ge_u32_e32 vcc, v3, v2
	s_nop 1
	v_cndmask_b32_e32 v1, v1, v4, vcc
	v_sub_u32_e32 v4, v3, v2
	v_cndmask_b32_e32 v3, v3, v4, vcc
	v_add_u32_e32 v4, 1, v1
	v_cmp_ge_u32_e32 vcc, v3, v2
	v_add_u32_e32 v3, 1, v5
	s_nop 0
	v_cndmask_b32_e32 v1, v1, v4, vcc
	v_mul_lo_u32 v4, v2, v1
	v_add_u32_e32 v2, v4, v2
	v_cmp_ne_u32_e32 vcc, v3, v2
	s_and_saveexec_b64 s[6:7], vcc
	s_xor_b64 s[6:7], exec, s[6:7]
	s_cbranch_execz .LBB0_130
	s_waitcnt lgkmcnt(0)
	v_mov_b32_e32 v235, 0x22804
	ds_read_b32 v235, v235
	v_add_u32_e32 v1, 1, v1
	s_waitcnt lgkmcnt(0)
	v_mul_lo_u32 v1, v1, v235
	v_mov_b32_e32 v0, 0x7400
	global_load_dword v0, v0, s[84:85] sc1
	s_add_u32 s12, s84, 0x7400
	s_addc_u32 s13, s85, 0
	s_waitcnt vmcnt(0)
	v_cmp_lt_u32_e32 vcc, v0, v1
	s_and_saveexec_b64 s[8:9], vcc
	s_cbranch_execz .LBB0_129
	s_add_u32 s10, s84, 0x4200
	s_addc_u32 s11, s85, 0
	s_mov_b32 s23, 1
	s_mov_b64 s[14:15], 0
	v_mov_b32_e32 v0, 0
	s_branch .LBB0_120

.LBB0_122:
	global_load_dword v2, v0, s[12:13] sc1
	s_add_i32 s23, s23, 1
	s_mov_b64 s[20:21], -1
	s_waitcnt vmcnt(0)
	v_cmp_ge_u32_e32 vcc, v2, v1
	s_orn2_b64 s[18:19], vcc, exec
	s_branch .LBB0_119

.LBB0_133:
	s_or_b64 exec, exec, s[10:11]
	v_cvt_f32_u32_e32 v3, v0
	s_waitcnt vmcnt(0)
	v_readfirstlane_b32 s8, v2
	s_add_u32 s10, s84, 0x7500
	s_addc_u32 s11, s85, 0
	v_rcp_iflag_f32_e32 v3, v3
	v_add_u32_e32 v1, s8, v1
	v_add_u32_e32 v4, 1, v1
	s_mov_b64 s[12:13], -1
	v_mul_f32_e32 v2, 0x4f7ffffe, v3
	v_cvt_u32_f32_e32 v2, v2
	v_sub_u32_e32 v3, 0, v0
	v_mul_lo_u32 v3, v3, v2
	v_mul_hi_u32 v3, v2, v3
	v_add_u32_e32 v2, v2, v3
	v_mul_hi_u32 v2, v1, v2
	v_mul_lo_u32 v3, v2, v0
	v_sub_u32_e32 v1, v1, v3
	v_add_u32_e32 v5, 1, v2
	v_cmp_ge_u32_e32 vcc, v1, v0
	v_sub_u32_e32 v3, v1, v0
	s_nop 0
	v_cndmask_b32_e32 v2, v2, v5, vcc
	v_cndmask_b32_e32 v1, v1, v3, vcc
	v_add_u32_e32 v3, 1, v2
	v_cmp_ge_u32_e32 vcc, v1, v0
	s_nop 1
	v_cndmask_b32_e32 v2, v2, v3, vcc
	v_mul_lo_u32 v1, v0, v2
	v_add_u32_e32 v0, v1, v0
	v_cmp_ne_u32_e32 vcc, v4, v0
	v_mov_b32_e32 v236, v0
	v_mov_b32_e32 v237, 0x7400
	v_mov_b64_e32 v[0:1], s[10:11]
	s_and_saveexec_b64 s[8:9], vcc
	s_cbranch_execz .LBB0_145
	v_mov_b32_e32 v0, 0
	global_load_dword v1, v237, s[84:85] sc1
	s_mov_b64 s[16:17], 0
	s_waitcnt vmcnt(0)
	v_cmp_lt_u32_e32 vcc, v1, v236
	s_and_saveexec_b64 s[14:15], vcc
	s_cbranch_execz .LBB0_144
	s_add_u32 s12, s84, 0x4200
	s_addc_u32 s13, s85, 0
	s_mov_b32 s23, 1
	s_branch .LBB0_137

.LBB0_139:
	global_load_dword v1, v237, s[84:85] sc1
	s_add_i32 s23, s23, 1
	s_mov_b64 s[20:21], -1
	s_waitcnt vmcnt(0)
	v_cmp_ge_u32_e32 vcc, v1, v236
	s_orn2_b64 s[26:27], vcc, exec
	s_branch .LBB0_136

.LBB0_231:
	s_or_b64 exec, exec, s[8:9]
	v_cvt_f32_u32_e32 v4, v2
	s_waitcnt vmcnt(0)
	v_readfirstlane_b32 s3, v3
	v_sub_u32_e32 v3, 0, v2
	v_rcp_iflag_f32_e32 v4, v4
	v_add_u32_e32 v5, s3, v1
	v_mul_f32_e32 v4, 0x4f7ffffe, v4
	v_cvt_u32_f32_e32 v4, v4
	v_mul_lo_u32 v1, v3, v4
	v_mul_hi_u32 v1, v4, v1
	v_add_u32_e32 v1, v4, v1
	v_mul_hi_u32 v1, v5, v1
	v_mul_lo_u32 v3, v1, v2
	v_sub_u32_e32 v3, v5, v3
	v_add_u32_e32 v4, 1, v1
	v_cmp_ge_u32_e32 vcc, v3, v2
	s_nop 1
	v_cndmask_b32_e32 v1, v1, v4, vcc
	v_sub_u32_e32 v4, v3, v2
	v_cndmask_b32_e32 v3, v3, v4, vcc
	v_add_u32_e32 v4, 1, v1
	v_cmp_ge_u32_e32 vcc, v3, v2
	v_add_u32_e32 v3, 1, v5
	s_nop 0
	v_cndmask_b32_e32 v1, v1, v4, vcc
	v_mul_lo_u32 v4, v2, v1
	v_add_u32_e32 v2, v4, v2
	v_cmp_ne_u32_e32 vcc, v3, v2
	s_and_saveexec_b64 s[6:7], vcc
	s_xor_b64 s[6:7], exec, s[6:7]
	s_cbranch_execz .LBB0_245
	s_waitcnt lgkmcnt(0)
	v_mov_b32_e32 v235, 0x22804
	ds_read_b32 v235, v235
	v_add_u32_e32 v1, 1, v1
	s_waitcnt lgkmcnt(0)
	v_mul_lo_u32 v1, v1, v235
	v_mov_b32_e32 v0, 0x7400
	global_load_dword v0, v0, s[84:85] sc1
	s_add_u32 s14, s84, 0x7400
	s_addc_u32 s15, s85, 0
	s_waitcnt vmcnt(0)
	v_cmp_lt_u32_e32 vcc, v0, v1
	s_and_saveexec_b64 s[8:9], vcc
	s_cbranch_execz .LBB0_244
	s_add_u32 s12, s84, 0x4200
	s_addc_u32 s13, s85, 0
	s_mov_b32 s3, 1
	s_mov_b64 s[16:17], 0
	v_mov_b32_e32 v0, 0
	s_branch .LBB0_235

.LBB0_237:
	global_load_dword v2, v0, s[14:15] sc1
	s_add_i32 s3, s3, 1
	s_mov_b64 s[26:27], -1
	s_waitcnt vmcnt(0)
	v_cmp_ge_u32_e32 vcc, v2, v1
	s_orn2_b64 s[24:25], vcc, exec
	s_branch .LBB0_234

.LBB0_248:
	s_or_b64 exec, exec, s[12:13]
	v_cvt_f32_u32_e32 v3, v0
	s_waitcnt vmcnt(0)
	v_readfirstlane_b32 s3, v2
	s_add_u32 s12, s84, 0x7500
	s_addc_u32 s13, s85, 0
	v_rcp_iflag_f32_e32 v3, v3
	v_add_u32_e32 v1, s3, v1
	v_add_u32_e32 v4, 1, v1
	s_mov_b64 s[14:15], -1
	v_mul_f32_e32 v2, 0x4f7ffffe, v3
	v_cvt_u32_f32_e32 v2, v2
	v_sub_u32_e32 v3, 0, v0
	v_mul_lo_u32 v3, v3, v2
	v_mul_hi_u32 v3, v2, v3
	v_add_u32_e32 v2, v2, v3
	v_mul_hi_u32 v2, v1, v2
	v_mul_lo_u32 v3, v2, v0
	v_sub_u32_e32 v1, v1, v3
	v_add_u32_e32 v5, 1, v2
	v_cmp_ge_u32_e32 vcc, v1, v0
	v_sub_u32_e32 v3, v1, v0
	s_nop 0
	v_cndmask_b32_e32 v2, v2, v5, vcc
	v_cndmask_b32_e32 v1, v1, v3, vcc
	v_add_u32_e32 v3, 1, v2
	v_cmp_ge_u32_e32 vcc, v1, v0
	s_nop 1
	v_cndmask_b32_e32 v2, v2, v3, vcc
	v_mul_lo_u32 v1, v0, v2
	v_add_u32_e32 v0, v1, v0
	v_cmp_ne_u32_e32 vcc, v4, v0
	v_mov_b32_e32 v236, v0
	v_mov_b32_e32 v237, 0x7400
	v_mov_b64_e32 v[0:1], s[12:13]
	s_and_saveexec_b64 s[8:9], vcc
	s_cbranch_execz .LBB0_260
	v_mov_b32_e32 v0, 0
	global_load_dword v1, v237, s[84:85] sc1
	s_mov_b64 s[20:21], 0
	s_waitcnt vmcnt(0)
	v_cmp_lt_u32_e32 vcc, v1, v236
	s_and_saveexec_b64 s[16:17], vcc
	s_cbranch_execz .LBB0_259
	s_add_u32 s14, s84, 0x4200
	s_addc_u32 s15, s85, 0
	s_mov_b32 s3, 1
	s_branch .LBB0_252

.LBB0_254:
	global_load_dword v1, v237, s[84:85] sc1
	s_add_i32 s3, s3, 1
	s_mov_b64 s[26:27], -1
	s_waitcnt vmcnt(0)
	v_cmp_ge_u32_e32 vcc, v1, v236
	s_orn2_b64 s[30:31], vcc, exec
	s_branch .LBB0_251

.LBB0_289:
	s_or_b64 exec, exec, s[8:9]
	v_cvt_f32_u32_e32 v4, v2
	s_waitcnt vmcnt(0)
	v_readfirstlane_b32 s3, v3
	v_sub_u32_e32 v3, 0, v2
	v_rcp_iflag_f32_e32 v4, v4
	v_add_u32_e32 v5, s3, v1
	v_mul_f32_e32 v4, 0x4f7ffffe, v4
	v_cvt_u32_f32_e32 v4, v4
	v_mul_lo_u32 v1, v3, v4
	v_mul_hi_u32 v1, v4, v1
	v_add_u32_e32 v1, v4, v1
	v_mul_hi_u32 v1, v5, v1
	v_mul_lo_u32 v3, v1, v2
	v_sub_u32_e32 v3, v5, v3
	v_add_u32_e32 v4, 1, v1
	v_cmp_ge_u32_e32 vcc, v3, v2
	s_nop 1
	v_cndmask_b32_e32 v1, v1, v4, vcc
	v_sub_u32_e32 v4, v3, v2
	v_cndmask_b32_e32 v3, v3, v4, vcc
	v_add_u32_e32 v4, 1, v1
	v_cmp_ge_u32_e32 vcc, v3, v2
	v_add_u32_e32 v3, 1, v5
	s_nop 0
	v_cndmask_b32_e32 v1, v1, v4, vcc
	v_mul_lo_u32 v4, v2, v1
	v_add_u32_e32 v2, v4, v2
	v_cmp_ne_u32_e32 vcc, v3, v2
	s_and_saveexec_b64 s[6:7], vcc
	s_xor_b64 s[6:7], exec, s[6:7]
	s_cbranch_execz .LBB0_303
	s_waitcnt lgkmcnt(0)
	v_mov_b32_e32 v235, 0x22804
	ds_read_b32 v235, v235
	v_add_u32_e32 v1, 1, v1
	s_waitcnt lgkmcnt(0)
	v_mul_lo_u32 v1, v1, v235
	v_mov_b32_e32 v0, 0x7400
	global_load_dword v0, v0, s[84:85] sc1
	s_add_u32 s14, s84, 0x7400
	s_addc_u32 s15, s85, 0
	s_waitcnt vmcnt(0)
	v_cmp_lt_u32_e32 vcc, v0, v1
	s_and_saveexec_b64 s[8:9], vcc
	s_cbranch_execz .LBB0_302
	s_add_u32 s12, s84, 0x4200
	s_addc_u32 s13, s85, 0
	s_mov_b32 s3, 1
	s_mov_b64 s[20:21], 0
	v_mov_b32_e32 v0, 0
	s_branch .LBB0_293

.LBB0_295:
	global_load_dword v2, v0, s[14:15] sc1
	s_add_i32 s3, s3, 1
	s_mov_b64 s[28:29], -1
	s_waitcnt vmcnt(0)
	v_cmp_ge_u32_e32 vcc, v2, v1
	s_orn2_b64 s[26:27], vcc, exec
	s_branch .LBB0_292

.LBB0_306:
	s_or_b64 exec, exec, s[12:13]
	v_cvt_f32_u32_e32 v3, v0
	s_waitcnt vmcnt(0)
	v_readfirstlane_b32 s3, v2
	s_add_u32 s12, s84, 0x7500
	s_addc_u32 s13, s85, 0
	v_rcp_iflag_f32_e32 v3, v3
	v_add_u32_e32 v1, s3, v1
	v_add_u32_e32 v4, 1, v1
	s_mov_b64 s[14:15], -1
	v_mul_f32_e32 v2, 0x4f7ffffe, v3
	v_cvt_u32_f32_e32 v2, v2
	v_sub_u32_e32 v3, 0, v0
	v_mul_lo_u32 v3, v3, v2
	v_mul_hi_u32 v3, v2, v3
	v_add_u32_e32 v2, v2, v3
	v_mul_hi_u32 v2, v1, v2
	v_mul_lo_u32 v3, v2, v0
	v_sub_u32_e32 v1, v1, v3
	v_add_u32_e32 v5, 1, v2
	v_cmp_ge_u32_e32 vcc, v1, v0
	v_sub_u32_e32 v3, v1, v0
	s_nop 0
	v_cndmask_b32_e32 v2, v2, v5, vcc
	v_cndmask_b32_e32 v1, v1, v3, vcc
	v_add_u32_e32 v3, 1, v2
	v_cmp_ge_u32_e32 vcc, v1, v0
	s_nop 1
	v_cndmask_b32_e32 v2, v2, v3, vcc
	v_mul_lo_u32 v1, v0, v2
	v_add_u32_e32 v0, v1, v0
	v_cmp_ne_u32_e32 vcc, v4, v0
	v_mov_b32_e32 v236, v0
	v_mov_b32_e32 v237, 0x7400
	v_mov_b64_e32 v[0:1], s[12:13]
	s_and_saveexec_b64 s[8:9], vcc
	s_cbranch_execz .LBB0_318
	v_mov_b32_e32 v0, 0
	global_load_dword v1, v237, s[84:85] sc1
	s_mov_b64 s[24:25], 0
	s_waitcnt vmcnt(0)
	v_cmp_lt_u32_e32 vcc, v1, v236
	s_and_saveexec_b64 s[20:21], vcc
	s_cbranch_execz .LBB0_317
	s_add_u32 s14, s84, 0x4200
	s_addc_u32 s15, s85, 0
	s_mov_b32 s3, 1
	s_branch .LBB0_310

.LBB0_312:
	global_load_dword v1, v237, s[84:85] sc1
	s_add_i32 s3, s3, 1
	s_mov_b64 s[28:29], -1
	s_waitcnt vmcnt(0)
	v_cmp_ge_u32_e32 vcc, v1, v236
	s_orn2_b64 s[34:35], vcc, exec
	s_branch .LBB0_309

.LBB0_354:
	s_or_b64 exec, exec, s[8:9]
	v_cvt_f32_u32_e32 v4, v2
	s_waitcnt vmcnt(0)
	v_readfirstlane_b32 s3, v3
	v_sub_u32_e32 v3, 0, v2
	v_rcp_iflag_f32_e32 v4, v4
	v_add_u32_e32 v5, s3, v1
	v_mul_f32_e32 v4, 0x4f7ffffe, v4
	v_cvt_u32_f32_e32 v4, v4
	v_mul_lo_u32 v1, v3, v4
	v_mul_hi_u32 v1, v4, v1
	v_add_u32_e32 v1, v4, v1
	v_mul_hi_u32 v1, v5, v1
	v_mul_lo_u32 v3, v1, v2
	v_sub_u32_e32 v3, v5, v3
	v_add_u32_e32 v4, 1, v1
	v_cmp_ge_u32_e32 vcc, v3, v2
	s_nop 1
	v_cndmask_b32_e32 v1, v1, v4, vcc
	v_sub_u32_e32 v4, v3, v2
	v_cndmask_b32_e32 v3, v3, v4, vcc
	v_add_u32_e32 v4, 1, v1
	v_cmp_ge_u32_e32 vcc, v3, v2
	v_add_u32_e32 v3, 1, v5
	s_nop 0
	v_cndmask_b32_e32 v1, v1, v4, vcc
	v_mul_lo_u32 v4, v2, v1
	v_add_u32_e32 v2, v4, v2
	v_cmp_ne_u32_e32 vcc, v3, v2
	s_and_saveexec_b64 s[6:7], vcc
	s_xor_b64 s[6:7], exec, s[6:7]
	s_cbranch_execz .LBB0_368
	s_waitcnt lgkmcnt(0)
	v_mov_b32_e32 v235, 0x22804
	ds_read_b32 v235, v235
	v_add_u32_e32 v1, 1, v1
	s_waitcnt lgkmcnt(0)
	v_mul_lo_u32 v1, v1, v235
	v_mov_b32_e32 v0, 0x7400
	global_load_dword v0, v0, s[84:85] sc1
	s_add_u32 s12, s84, 0x7400
	s_addc_u32 s13, s85, 0
	s_waitcnt vmcnt(0)
	v_cmp_lt_u32_e32 vcc, v0, v1
	s_and_saveexec_b64 s[8:9], vcc
	s_cbranch_execz .LBB0_367
	s_add_u32 s10, s84, 0x4200
	s_addc_u32 s11, s85, 0
	s_mov_b32 s3, 1
	s_mov_b64 s[14:15], 0
	v_mov_b32_e32 v0, 0
	s_branch .LBB0_358

.LBB0_360:
	global_load_dword v2, v0, s[12:13] sc1
	s_add_i32 s3, s3, 1
	s_mov_b64 s[26:27], -1
	s_waitcnt vmcnt(0)
	v_cmp_ge_u32_e32 vcc, v2, v1
	s_orn2_b64 s[24:25], vcc, exec
	s_branch .LBB0_357

.LBB0_371:
	s_or_b64 exec, exec, s[10:11]
	v_cvt_f32_u32_e32 v3, v0
	s_waitcnt vmcnt(0)
	v_readfirstlane_b32 s3, v2
	s_add_u32 s10, s84, 0x7500
	s_addc_u32 s11, s85, 0
	v_rcp_iflag_f32_e32 v3, v3
	v_add_u32_e32 v1, s3, v1
	v_add_u32_e32 v4, 1, v1
	s_mov_b64 s[12:13], -1
	v_mul_f32_e32 v2, 0x4f7ffffe, v3
	v_cvt_u32_f32_e32 v2, v2
	v_sub_u32_e32 v3, 0, v0
	v_mul_lo_u32 v3, v3, v2
	v_mul_hi_u32 v3, v2, v3
	v_add_u32_e32 v2, v2, v3
	v_mul_hi_u32 v2, v1, v2
	v_mul_lo_u32 v3, v2, v0
	v_sub_u32_e32 v1, v1, v3
	v_add_u32_e32 v5, 1, v2
	v_cmp_ge_u32_e32 vcc, v1, v0
	v_sub_u32_e32 v3, v1, v0
	s_nop 0
	v_cndmask_b32_e32 v2, v2, v5, vcc
	v_cndmask_b32_e32 v1, v1, v3, vcc
	v_add_u32_e32 v3, 1, v2
	v_cmp_ge_u32_e32 vcc, v1, v0
	s_nop 1
	v_cndmask_b32_e32 v2, v2, v3, vcc
	v_mul_lo_u32 v1, v0, v2
	v_add_u32_e32 v0, v1, v0
	v_cmp_ne_u32_e32 vcc, v4, v0
	v_mov_b32_e32 v236, v0
	v_mov_b32_e32 v237, 0x7400
	v_mov_b64_e32 v[0:1], s[10:11]
	s_and_saveexec_b64 s[8:9], vcc
	s_cbranch_execz .LBB0_383
	v_mov_b32_e32 v0, 0
	global_load_dword v1, v237, s[84:85] sc1
	s_mov_b64 s[20:21], 0
	s_waitcnt vmcnt(0)
	v_cmp_lt_u32_e32 vcc, v1, v236
	s_and_saveexec_b64 s[14:15], vcc
	s_cbranch_execz .LBB0_382
	s_add_u32 s12, s84, 0x4200
	s_addc_u32 s13, s85, 0
	s_mov_b32 s3, 1
	s_branch .LBB0_375

.LBB0_843:
	global_load_dword v2, v0, s[12:13] sc1
	s_add_i32 s3, s3, 1
	s_mov_b64 s[24:25], -1
	s_waitcnt vmcnt(0)
	v_cmp_ge_u32_e32 vcc, v2, v1
	s_orn2_b64 s[20:21], vcc, exec
	s_branch .LBB0_840

.LBB0_854:
	s_or_b64 exec, exec, s[10:11]
	v_cvt_f32_u32_e32 v3, v0
	s_waitcnt vmcnt(0)
	v_readfirstlane_b32 s3, v2
	s_add_u32 s10, s84, 0x7500
	s_addc_u32 s11, s85, 0
	v_rcp_iflag_f32_e32 v3, v3
	v_add_u32_e32 v1, s3, v1
	v_add_u32_e32 v4, 1, v1
	s_mov_b64 s[12:13], -1
	v_mul_f32_e32 v2, 0x4f7ffffe, v3
	v_cvt_u32_f32_e32 v2, v2
	v_sub_u32_e32 v3, 0, v0
	v_mul_lo_u32 v3, v3, v2
	v_mul_hi_u32 v3, v2, v3
	v_add_u32_e32 v2, v2, v3
	v_mul_hi_u32 v2, v1, v2
	v_mul_lo_u32 v3, v2, v0
	v_sub_u32_e32 v1, v1, v3
	v_add_u32_e32 v5, 1, v2
	v_cmp_ge_u32_e32 vcc, v1, v0
	v_sub_u32_e32 v3, v1, v0
	s_nop 0
	v_cndmask_b32_e32 v2, v2, v5, vcc
	v_cndmask_b32_e32 v1, v1, v3, vcc
	v_add_u32_e32 v3, 1, v2
	v_cmp_ge_u32_e32 vcc, v1, v0
	s_nop 1
	v_cndmask_b32_e32 v2, v2, v3, vcc
	v_mul_lo_u32 v1, v0, v2
	v_add_u32_e32 v0, v1, v0
	v_cmp_ne_u32_e32 vcc, v4, v0
	v_mov_b32_e32 v236, v0
	v_mov_b32_e32 v237, 0x7400
	v_mov_b64_e32 v[0:1], s[10:11]
	s_and_saveexec_b64 s[8:9], vcc
	s_cbranch_execz .LBB0_866
	v_mov_b32_e32 v0, 0
	global_load_dword v1, v237, s[84:85] sc1
	s_mov_b64 s[18:19], 0
	s_waitcnt vmcnt(0)
	v_cmp_lt_u32_e32 vcc, v1, v236
	s_and_saveexec_b64 s[14:15], vcc
	s_cbranch_execz .LBB0_865
	s_add_u32 s12, s84, 0x4200
	s_addc_u32 s13, s85, 0
	s_mov_b32 s3, 1
	s_branch .LBB0_858

.LBB0_860:
	global_load_dword v1, v237, s[84:85] sc1
	s_add_i32 s3, s3, 1
	s_mov_b64 s[24:25], -1
	s_waitcnt vmcnt(0)
	v_cmp_ge_u32_e32 vcc, v1, v236
	s_orn2_b64 s[28:29], vcc, exec
	s_branch .LBB0_857

.LBB0_951:
	global_load_dword v2, v0, s[12:13] sc1
	s_add_i32 s3, s3, 1
	s_mov_b64 s[20:21], -1
	s_waitcnt vmcnt(0)
	v_cmp_ge_u32_e32 vcc, v2, v1
	s_orn2_b64 s[18:19], vcc, exec
	s_branch .LBB0_948

.LBB0_962:
	s_or_b64 exec, exec, s[10:11]
	v_cvt_f32_u32_e32 v3, v0
	s_waitcnt vmcnt(0)
	v_readfirstlane_b32 s3, v2
	s_add_u32 s10, s84, 0x7500
	s_addc_u32 s11, s85, 0
	v_rcp_iflag_f32_e32 v3, v3
	v_add_u32_e32 v1, s3, v1
	v_add_u32_e32 v4, 1, v1
	s_mov_b64 s[12:13], -1
	v_mul_f32_e32 v2, 0x4f7ffffe, v3
	v_cvt_u32_f32_e32 v2, v2
	v_sub_u32_e32 v3, 0, v0
	v_mul_lo_u32 v3, v3, v2
	v_mul_hi_u32 v3, v2, v3
	v_add_u32_e32 v2, v2, v3
	v_mul_hi_u32 v2, v1, v2
	v_mul_lo_u32 v3, v2, v0
	v_sub_u32_e32 v1, v1, v3
	v_add_u32_e32 v5, 1, v2
	v_cmp_ge_u32_e32 vcc, v1, v0
	v_sub_u32_e32 v3, v1, v0
	s_nop 0
	v_cndmask_b32_e32 v2, v2, v5, vcc
	v_cndmask_b32_e32 v1, v1, v3, vcc
	v_add_u32_e32 v3, 1, v2
	v_cmp_ge_u32_e32 vcc, v1, v0
	s_nop 1
	v_cndmask_b32_e32 v2, v2, v3, vcc
	v_mul_lo_u32 v1, v0, v2
	v_add_u32_e32 v0, v1, v0
	v_cmp_ne_u32_e32 vcc, v4, v0
	v_mov_b32_e32 v236, v0
	v_mov_b32_e32 v237, 0x7400
	v_mov_b64_e32 v[0:1], s[10:11]
	s_and_saveexec_b64 s[8:9], vcc
	s_cbranch_execz .LBB0_974
	v_mov_b32_e32 v0, 0
	global_load_dword v1, v237, s[84:85] sc1
	s_mov_b64 s[16:17], 0
	s_waitcnt vmcnt(0)
	v_cmp_lt_u32_e32 vcc, v1, v236
	s_and_saveexec_b64 s[14:15], vcc
	s_cbranch_execz .LBB0_973
	s_add_u32 s12, s84, 0x4200
	s_addc_u32 s13, s85, 0
	s_mov_b32 s3, 1
	s_branch .LBB0_966

.LBB0_968:
	global_load_dword v1, v237, s[84:85] sc1
	s_add_i32 s3, s3, 1
	s_mov_b64 s[20:21], -1
	s_waitcnt vmcnt(0)
	v_cmp_ge_u32_e32 vcc, v1, v236
	s_orn2_b64 s[26:27], vcc, exec
	s_branch .LBB0_965

.LBB0_1084:
	s_or_b64 exec, exec, s[12:13]
	v_cvt_f32_u32_e32 v4, v2
	s_waitcnt vmcnt(0)
	v_readfirstlane_b32 s3, v3
	v_sub_u32_e32 v3, 0, v2
	v_rcp_iflag_f32_e32 v4, v4
	v_add_u32_e32 v5, s3, v1
	v_mul_f32_e32 v4, 0x4f7ffffe, v4
	v_cvt_u32_f32_e32 v4, v4
	v_mul_lo_u32 v1, v3, v4
	v_mul_hi_u32 v1, v4, v1
	v_add_u32_e32 v1, v4, v1
	v_mul_hi_u32 v1, v5, v1
	v_mul_lo_u32 v3, v1, v2
	v_sub_u32_e32 v3, v5, v3
	v_add_u32_e32 v4, 1, v1
	v_cmp_ge_u32_e32 vcc, v3, v2
	s_nop 1
	v_cndmask_b32_e32 v1, v1, v4, vcc
	v_sub_u32_e32 v4, v3, v2
	v_cndmask_b32_e32 v3, v3, v4, vcc
	v_add_u32_e32 v4, 1, v1
	v_cmp_ge_u32_e32 vcc, v3, v2
	v_add_u32_e32 v3, 1, v5
	s_nop 0
	v_cndmask_b32_e32 v1, v1, v4, vcc
	v_mul_lo_u32 v4, v2, v1
	v_add_u32_e32 v2, v4, v2
	v_cmp_ne_u32_e32 vcc, v3, v2
	s_and_saveexec_b64 s[10:11], vcc
	s_xor_b64 s[10:11], exec, s[10:11]
	s_cbranch_execz .LBB0_1098
	s_waitcnt lgkmcnt(0)
	v_mov_b32_e32 v235, 0x22804
	ds_read_b32 v235, v235
	v_add_u32_e32 v1, 1, v1
	s_waitcnt lgkmcnt(0)
	v_mul_lo_u32 v1, v1, v235
	v_mov_b32_e32 v0, 0x7400
	global_load_dword v0, v0, s[84:85] sc1
	s_add_u32 s16, s84, 0x7400
	s_addc_u32 s17, s85, 0
	s_waitcnt vmcnt(0)
	v_cmp_lt_u32_e32 vcc, v0, v1
	s_and_saveexec_b64 s[12:13], vcc
	s_cbranch_execz .LBB0_1097
	s_add_u32 s14, s84, 0x4200
	s_addc_u32 s15, s85, 0
	s_mov_b32 s3, 1
	s_mov_b64 s[18:19], 0
	v_mov_b32_e32 v0, 0
	s_branch .LBB0_1088

.LBB0_1090:
	global_load_dword v2, v0, s[16:17] sc1
	s_add_i32 s3, s3, 1
	s_mov_b64 s[26:27], -1
	s_waitcnt vmcnt(0)
	v_cmp_ge_u32_e32 vcc, v2, v1
	s_orn2_b64 s[24:25], vcc, exec
	s_branch .LBB0_1087

.LBB0_1101:
	s_or_b64 exec, exec, s[12:13]
	v_cvt_f32_u32_e32 v3, v0
	s_waitcnt vmcnt(0)
	v_readfirstlane_b32 s3, v2
	s_add_u32 s12, s84, 0x7500
	s_addc_u32 s13, s85, 0
	v_rcp_iflag_f32_e32 v3, v3
	v_add_u32_e32 v1, s3, v1
	v_add_u32_e32 v4, 1, v1
	s_mov_b64 s[14:15], -1
	v_mul_f32_e32 v2, 0x4f7ffffe, v3
	v_cvt_u32_f32_e32 v2, v2
	v_sub_u32_e32 v3, 0, v0
	v_mul_lo_u32 v3, v3, v2
	v_mul_hi_u32 v3, v2, v3
	v_add_u32_e32 v2, v2, v3
	v_mul_hi_u32 v2, v1, v2
	v_mul_lo_u32 v3, v2, v0
	v_sub_u32_e32 v1, v1, v3
	v_add_u32_e32 v5, 1, v2
	v_cmp_ge_u32_e32 vcc, v1, v0
	v_sub_u32_e32 v3, v1, v0
	s_nop 0
	v_cndmask_b32_e32 v2, v2, v5, vcc
	v_cndmask_b32_e32 v1, v1, v3, vcc
	v_add_u32_e32 v3, 1, v2
	v_cmp_ge_u32_e32 vcc, v1, v0
	s_nop 1
	v_cndmask_b32_e32 v2, v2, v3, vcc
	v_mul_lo_u32 v1, v0, v2
	v_add_u32_e32 v0, v1, v0
	v_cmp_ne_u32_e32 vcc, v4, v0
	v_mov_b32_e32 v236, v0
	v_mov_b32_e32 v237, 0x7400
	v_mov_b64_e32 v[0:1], s[12:13]
	s_and_saveexec_b64 s[10:11], vcc
	s_cbranch_execz .LBB0_1113
	v_mov_b32_e32 v0, 0
	global_load_dword v1, v237, s[84:85] sc1
	s_mov_b64 s[18:19], 0
	s_waitcnt vmcnt(0)
	v_cmp_lt_u32_e32 vcc, v1, v236
	s_and_saveexec_b64 s[16:17], vcc
	s_cbranch_execz .LBB0_1112
	s_add_u32 s14, s84, 0x4200
	s_addc_u32 s15, s85, 0
	s_mov_b32 s3, 1
	s_branch .LBB0_1105

.LBB0_1297:
	s_or_b64 exec, exec, s[8:9]
	v_cvt_f32_u32_e32 v4, v2
	s_waitcnt vmcnt(0)
	v_readfirstlane_b32 s6, v3
	v_sub_u32_e32 v3, 0, v2
	v_rcp_iflag_f32_e32 v4, v4
	v_add_u32_e32 v5, s6, v1
	v_mul_f32_e32 v4, 0x4f7ffffe, v4
	v_cvt_u32_f32_e32 v4, v4
	v_mul_lo_u32 v1, v3, v4
	v_mul_hi_u32 v1, v4, v1
	v_add_u32_e32 v1, v4, v1
	v_mul_hi_u32 v1, v5, v1
	v_mul_lo_u32 v3, v1, v2
	v_sub_u32_e32 v3, v5, v3
	v_add_u32_e32 v4, 1, v1
	v_cmp_ge_u32_e32 vcc, v3, v2
	s_nop 1
	v_cndmask_b32_e32 v1, v1, v4, vcc
	v_sub_u32_e32 v4, v3, v2
	v_cndmask_b32_e32 v3, v3, v4, vcc
	v_add_u32_e32 v4, 1, v1
	v_cmp_ge_u32_e32 vcc, v3, v2
	v_add_u32_e32 v3, 1, v5
	s_nop 0
	v_cndmask_b32_e32 v1, v1, v4, vcc
	v_mul_lo_u32 v4, v2, v1
	v_add_u32_e32 v2, v4, v2
	v_cmp_ne_u32_e32 vcc, v3, v2
	s_and_saveexec_b64 s[6:7], vcc
	s_xor_b64 s[6:7], exec, s[6:7]
	s_cbranch_execz .LBB0_1311
	s_waitcnt lgkmcnt(0)
	v_mov_b32_e32 v235, 0x22804
	ds_read_b32 v235, v235
	v_add_u32_e32 v1, 1, v1
	s_waitcnt lgkmcnt(0)
	v_mul_lo_u32 v1, v1, v235
	v_mov_b32_e32 v0, 0x7400
	global_load_dword v0, v0, s[84:85] sc1
	s_add_u32 s12, s84, 0x7400
	s_addc_u32 s13, s85, 0
	s_waitcnt vmcnt(0)
	v_cmp_lt_u32_e32 vcc, v0, v1
	s_and_saveexec_b64 s[8:9], vcc
	s_cbranch_execz .LBB0_1310
	s_add_u32 s10, s84, 0x4200
	s_addc_u32 s11, s85, 0
	s_mov_b32 s22, 1
	s_mov_b64 s[14:15], 0
	v_mov_b32_e32 v0, 0
	s_branch .LBB0_1301

.LBB0_1303:
	global_load_dword v2, v0, s[12:13] sc1
	s_add_i32 s22, s22, 1
	s_mov_b64 s[20:21], -1
	s_waitcnt vmcnt(0)
	v_cmp_ge_u32_e32 vcc, v2, v1
	s_orn2_b64 s[18:19], vcc, exec
	s_branch .LBB0_1300

.LBB0_1314:
	s_or_b64 exec, exec, s[10:11]
	v_cvt_f32_u32_e32 v3, v0
	s_waitcnt vmcnt(0)
	v_readfirstlane_b32 s8, v2
	s_add_u32 s10, s84, 0x7500
	s_addc_u32 s11, s85, 0
	v_rcp_iflag_f32_e32 v3, v3
	v_add_u32_e32 v1, s8, v1
	v_add_u32_e32 v4, 1, v1
	s_mov_b64 s[12:13], -1
	v_mul_f32_e32 v2, 0x4f7ffffe, v3
	v_cvt_u32_f32_e32 v2, v2
	v_sub_u32_e32 v3, 0, v0
	v_mul_lo_u32 v3, v3, v2
	v_mul_hi_u32 v3, v2, v3
	v_add_u32_e32 v2, v2, v3
	v_mul_hi_u32 v2, v1, v2
	v_mul_lo_u32 v3, v2, v0
	v_sub_u32_e32 v1, v1, v3
	v_add_u32_e32 v5, 1, v2
	v_cmp_ge_u32_e32 vcc, v1, v0
	v_sub_u32_e32 v3, v1, v0
	s_nop 0
	v_cndmask_b32_e32 v2, v2, v5, vcc
	v_cndmask_b32_e32 v1, v1, v3, vcc
	v_add_u32_e32 v3, 1, v2
	v_cmp_ge_u32_e32 vcc, v1, v0
	s_nop 1
	v_cndmask_b32_e32 v2, v2, v3, vcc
	v_mul_lo_u32 v1, v0, v2
	v_add_u32_e32 v0, v1, v0
	v_cmp_ne_u32_e32 vcc, v4, v0
	v_mov_b32_e32 v236, v0
	v_mov_b32_e32 v237, 0x7400
	v_mov_b64_e32 v[0:1], s[10:11]
	s_and_saveexec_b64 s[8:9], vcc
	s_cbranch_execz .LBB0_1326
	v_mov_b32_e32 v0, 0
	global_load_dword v1, v237, s[84:85] sc1
	s_mov_b64 s[16:17], 0
	s_waitcnt vmcnt(0)
	v_cmp_lt_u32_e32 vcc, v1, v236
	s_and_saveexec_b64 s[14:15], vcc
	s_cbranch_execz .LBB0_1325
	s_add_u32 s12, s84, 0x4200
	s_addc_u32 s13, s85, 0
	s_mov_b32 s22, 1
	s_branch .LBB0_1318

.LBB0_1320:
	global_load_dword v1, v237, s[84:85] sc1
	s_add_i32 s22, s22, 1
	s_mov_b64 s[20:21], -1
	s_waitcnt vmcnt(0)
	v_cmp_ge_u32_e32 vcc, v1, v236
	s_orn2_b64 s[26:27], vcc, exec
	s_branch .LBB0_1317

.LBB0_1374:
	s_or_b64 exec, exec, s[6:7]
	v_cvt_f32_u32_e32 v4, v2
	s_waitcnt vmcnt(0)
	v_readfirstlane_b32 s4, v3
	v_sub_u32_e32 v3, 0, v2
	v_rcp_iflag_f32_e32 v4, v4
	v_add_u32_e32 v5, s4, v1
	v_mul_f32_e32 v4, 0x4f7ffffe, v4
	v_cvt_u32_f32_e32 v4, v4
	v_mul_lo_u32 v1, v3, v4
	v_mul_hi_u32 v1, v4, v1
	v_add_u32_e32 v1, v4, v1
	v_mul_hi_u32 v1, v5, v1
	v_mul_lo_u32 v3, v1, v2
	v_sub_u32_e32 v3, v5, v3
	v_add_u32_e32 v4, 1, v1
	v_cmp_ge_u32_e32 vcc, v3, v2
	s_nop 1
	v_cndmask_b32_e32 v1, v1, v4, vcc
	v_sub_u32_e32 v4, v3, v2
	v_cndmask_b32_e32 v3, v3, v4, vcc
	v_add_u32_e32 v4, 1, v1
	v_cmp_ge_u32_e32 vcc, v3, v2
	v_add_u32_e32 v3, 1, v5
	s_nop 0
	v_cndmask_b32_e32 v1, v1, v4, vcc
	v_mul_lo_u32 v4, v2, v1
	v_add_u32_e32 v2, v4, v2
	v_cmp_ne_u32_e32 vcc, v3, v2
	s_and_saveexec_b64 s[4:5], vcc
	s_xor_b64 s[4:5], exec, s[4:5]
	s_cbranch_execz .LBB0_1388
	s_waitcnt lgkmcnt(0)
	v_mov_b32_e32 v235, 0x22804
	ds_read_b32 v235, v235
	v_add_u32_e32 v1, 1, v1
	s_waitcnt lgkmcnt(0)
	v_mul_lo_u32 v1, v1, v235
	v_mov_b32_e32 v0, 0x7400
	global_load_dword v0, v0, s[84:85] sc1
	s_add_u32 s10, s84, 0x7400
	s_addc_u32 s11, s85, 0
	s_waitcnt vmcnt(0)
	v_cmp_lt_u32_e32 vcc, v0, v1
	s_and_saveexec_b64 s[6:7], vcc
	s_cbranch_execz .LBB0_1387
	s_add_u32 s8, s84, 0x4200
	s_addc_u32 s9, s85, 0
	s_mov_b32 s22, 1
	s_mov_b64 s[12:13], 0
	v_mov_b32_e32 v0, 0
	s_branch .LBB0_1378

.LBB0_1380:
	global_load_dword v2, v0, s[10:11] sc1
	s_add_i32 s22, s22, 1
	s_mov_b64 s[18:19], -1
	s_waitcnt vmcnt(0)
	v_cmp_ge_u32_e32 vcc, v2, v1
	s_orn2_b64 s[16:17], vcc, exec
	s_branch .LBB0_1377

.LBB0_1391:
	s_or_b64 exec, exec, s[8:9]
	v_cvt_f32_u32_e32 v3, v0
	s_waitcnt vmcnt(0)
	v_readfirstlane_b32 s6, v2
	s_add_u32 s8, s84, 0x7500
	s_addc_u32 s9, s85, 0
	v_rcp_iflag_f32_e32 v3, v3
	v_add_u32_e32 v1, s6, v1
	v_add_u32_e32 v4, 1, v1
	s_mov_b64 s[10:11], -1
	v_mul_f32_e32 v2, 0x4f7ffffe, v3
	v_cvt_u32_f32_e32 v2, v2
	v_sub_u32_e32 v3, 0, v0
	v_mul_lo_u32 v3, v3, v2
	v_mul_hi_u32 v3, v2, v3
	v_add_u32_e32 v2, v2, v3
	v_mul_hi_u32 v2, v1, v2
	v_mul_lo_u32 v3, v2, v0
	v_sub_u32_e32 v1, v1, v3
	v_add_u32_e32 v5, 1, v2
	v_cmp_ge_u32_e32 vcc, v1, v0
	v_sub_u32_e32 v3, v1, v0
	s_nop 0
	v_cndmask_b32_e32 v2, v2, v5, vcc
	v_cndmask_b32_e32 v1, v1, v3, vcc
	v_add_u32_e32 v3, 1, v2
	v_cmp_ge_u32_e32 vcc, v1, v0
	s_nop 1
	v_cndmask_b32_e32 v2, v2, v3, vcc
	v_mul_lo_u32 v1, v0, v2
	v_add_u32_e32 v0, v1, v0
	v_cmp_ne_u32_e32 vcc, v4, v0
	v_mov_b32_e32 v236, v0
	v_mov_b32_e32 v237, 0x7400
	v_mov_b64_e32 v[0:1], s[8:9]
	s_and_saveexec_b64 s[6:7], vcc
	s_cbranch_execz .LBB0_1403
	v_mov_b32_e32 v0, 0
	global_load_dword v1, v237, s[84:85] sc1
	s_mov_b64 s[14:15], 0
	s_waitcnt vmcnt(0)
	v_cmp_lt_u32_e32 vcc, v1, v236
	s_and_saveexec_b64 s[12:13], vcc
	s_cbranch_execz .LBB0_1402
	s_add_u32 s10, s84, 0x4200
	s_addc_u32 s11, s85, 0
	s_mov_b32 s24, 1
	s_branch .LBB0_1395

.LBB0_1397:
	global_load_dword v1, v237, s[84:85] sc1
	s_add_i32 s24, s24, 1
	s_mov_b64 s[18:19], -1
	s_waitcnt vmcnt(0)
	v_cmp_ge_u32_e32 vcc, v1, v236
	s_orn2_b64 s[22:23], vcc, exec
	s_branch .LBB0_1394
